# HGRN interleaved loads in SGPR-base form with one 32-bit offset add per row; attention loop: DMA saddr form, 3 moves removed, +0x3000 hoisted from 8 address adds
# speedup vs baseline: 1.0092x; 1.0092x over previous
; template <bool SAFE>
; __device__ void phase_attn(const Params& p, const bf16_t* Qall, const bf16_t* Kall, const bf16_t* Vt, bf16_t* CAT, LAS unsigned char* lds) {
;   const int tid = threadIdx.x, w = __builtin_amdgcn_readfirstlane(tid >> 6), lane = tid & 63, r = lane & 31, hh = lane >> 5;
;   constexpr int KROW = 104, VROW = 72;
;   constexpr int KBYTES = 64 * KROW * 2, VBYTES = 64 * VROW * 2, BUF = KBYTES + VBYTES;
;   unsigned soff[3];
; #pragma unroll
;   for (int j = 0; j < 3; ++j) {
;     const int ci = (3 * w + j) * 64 + lane;
;     if (3 * w + j < 13) { const int row = ci / 13, part = ci % 13; soff[j] = (unsigned)(row * 96 + (part < 12 ? part : 0) * 8) * 2u; }
;     else { const int c2 = ci - 832, dv = c2 / 9, part = c2 % 9; soff[j] = (unsigned)((dv < 64 ? dv : 0) * NKEY + (part < 8 ? part : 0) * 8) * 2u; }
;   }
;     ...
;   for (int it = blockIdx.x; it < 544; it += gridDim.x) {
;     if (SAFE && p.aflag[it] == 0u) continue;
;     bool wbad = false;
;     int b, h, q0, nk, nq;
;     if (it < 512) { b = it >> 7; h = (it >> 4) & 7; q0 = 256 + (it & 15) * 512; nk = NKEY; nq = 512; }
;     else { const int i2 = it - 512; b = i2 >> 3; h = i2 & 7; q0 = 0; nk = 256; nq = 256; }
;     const size_t bh = (size_t)(b * 8 + h);
;     const int qw = 64 * w;
;     const bool wact = qw < nq;
;     const int qbase = q0 + (wact ? qw : 0) + r;
;     bf16x8 qf[2][6];
; #pragma unroll
;     for (int qb = 0; qb < 2; ++qb) {
;       const bf16_t* qp = Qall + (bh * NKEY + qbase + 32 * qb) * 96 + 8 * hh;
; #pragma unroll
;       for (int c = 0; c < 6; ++c) qf[qb][c] = *(const bf16x8*)(qp + 16 * c);
;     }
;     f32x16 o[2][2];
; #pragma unroll
;     for (int qb = 0; qb < 2; ++qb)
; #pragma unroll
;       for (int i = 0; i < 16; ++i) { o[qb][0][i] = 0.f; o[qb][1][i] = 0.f; }
;     float mrun[2] = {0.f, 0.f}, lrun[2] = {0.f, 0.f};
;     const bf16_t* kbase = Kall + bh * NKEY * 96;
;     const bf16_t* vbase = Vt + bh * 64 * NKEY;
;     ATT_STAGE(0, 0);
;     asm volatile("s_waitcnt vmcnt(0)" ::: "memory");
;     __syncthreads();
;     const int ntile = nk >> 6;
.LBB0_1246:
	s_cmpk_lt_i32 s92, 0x220
	s_cbranch_scc0 .LBB0_1268
	s_load_dwordx4 s[12:15], s[90:91], 0x150
	s_load_dwordx2 s[18:19], s[90:91], 0x148
	v_lshlrev_b32_e32 v184, 1, v2
	v_lshrrev_b32_e32 v2, 5, v6
	v_lshlrev_b32_e32 v186, 4, v2
	s_waitcnt lgkmcnt(0)
	s_add_u32 s2, s14, 0xb580000
	s_addc_u32 s3, s15, 0
	s_add_u32 s30, s14, 0xe700000
	v_mov_b32_e32 v187, 0
	v_lshlrev_b32_e32 v182, 1, v0
	v_and_b32_e32 v177, 31, v176
	s_addc_u32 s31, s15, 0
	s_and_b32 s33, s5, 0xffffffc0
	v_lshl_add_u64 v[0:1], s[14:15], 0, v[186:187]
	s_mov_b64 s[0:1], 0x8400000
	v_lshlrev_b32_e32 v3, 3, v2
	v_lshl_add_u64 v[188:189], v[0:1], 0, s[0:1]
	s_cmpk_lt_u32 s5, 0x1c0
	v_mul_u32_u24_e32 v0, 0x68, v177
	v_lshlrev_b32_e32 v190, 2, v2
	s_movk_i32 s5, 0x48
	v_mul_u32_u24_e32 v1, 0x48, v177
	v_mov_b32_e32 v2, 0x900
	v_mad_u32_u24 v2, v177, s5, v2
	v_add_lshl_u32 v179, v3, v0, 1
	v_or_b32_e32 v0, v190, v1
	v_lshlrev_b32_e32 v191, 1, v0
	v_or_b32_e32 v0, v2, v190
	s_cselect_b64 s[0:1], -1, 0
	s_add_u32 s22, s90, 0x168
	v_lshlrev_b32_e32 v196, 1, v0
	v_or_b32_e32 v0, 16, v190
	s_addc_u32 s23, s91, 0
	s_lshl_b32 s35, s8, 10
	s_lshl_b32 s36, s9, 10
	v_add_lshl_u32 v197, v0, v1, 1
	v_add_lshl_u32 v198, v0, v2, 1
	v_or_b32_e32 v0, 32, v190
	v_add_lshl_u32 v199, v0, v1, 1
	v_add_lshl_u32 v200, v0, v2, 1
	v_or_b32_e32 v0, 48, v190
	s_add_u32 s37, s14, 0xb583000
	v_add_lshl_u32 v201, v0, v1, 1
	v_add_lshl_u32 v202, v0, v2, 1
	s_addc_u32 s38, s15, 0
	v_cndmask_b32_e64 v0, 0, 1, s[0:1]
	s_mul_i32 s34, s4, 0xc00
	s_add_u32 s39, s14, 0xe700080
	v_cmp_ne_u32_e64 s[8:9], 1, v0
	v_mbcnt_lo_u32_b32 v0, -1, 0
	v_lshlrev_b32_e32 v180, 1, v4
	s_mov_b32 s21, 0
	v_cmp_eq_u32_e64 s[6:7], 0, v6
	v_mov_b32_e32 v183, v187
	v_mov_b32_e32 v181, v187
	v_mov_b32_e32 v185, v187
	s_addc_u32 s40, s15, 0
	s_movk_i32 s41, 0x100
	v_mov_b32_e32 v203, 0x2100
	s_movk_i32 s42, 0xc0
	s_movk_i32 s43, 0x1000
	s_mov_b32 s44, 0x67800000
	v_mov_b32_e32 v204, 1
	s_mov_b32 s45, 0x21800000
	s_movk_i32 s46, 0xe0
	s_add_i32 s47, s34, 0
	v_mbcnt_hi_u32_b32 v205, -1, v0
	s_mov_b32 s14, s92
	v_add_u32_e32 v248, 0x3000, v191
	v_add_u32_e32 v249, 0x3000, v196
	v_add_u32_e32 v250, 0x3000, v197
	v_add_u32_e32 v251, 0x3000, v198
	v_add_u32_e32 v252, 0x3000, v199
	v_add_u32_e32 v253, 0x3000, v200
	v_add_u32_e32 v254, 0x3000, v201
	v_add_u32_e32 v255, 0x3000, v202
	s_branch .LBB0_1250

; #define LAS __attribute__((address_space(3)))
; template <bool SAFE>
; __device__ void phase_attn(const Params& p, const bf16_t* Qall, const bf16_t* Kall, const bf16_t* Vt, bf16_t* CAT, LAS unsigned char* lds) {
;     ...
;       for (int c = 0; c < 6; ++c) {
;         const bf16x8 ka = *(const LAS bf16x8*)(kb_ + (r * KROW + 16 * c + 8 * hh) * 2);
;         const bf16x8 kb2 = *(const LAS bf16x8*)(kb_ + ((32 + r) * KROW + 16 * c + 8 * hh) * 2);
; #pragma unroll
;         for (int qb = 0; qb < 2; ++qb) {
;           s[qb][0] = __builtin_amdgcn_mfma_f32_32x32x16_bf16(ka, qf[qb][c], s[qb][0], 0, 0, 0);
;           s[qb][1] = __builtin_amdgcn_mfma_f32_32x32x16_bf16(kb2, qf[qb][c], s[qb][1], 0, 0, 0);
;         }
;       }
; #pragma unroll
;       for (int qb = 0; qb < 2; ++qb) {
;         if (SAFE) {
;           float mx = fmaxf(s[qb][0][0], s[qb][1][0]);
; #pragma unroll
;           for (int e = 1; e < 16; ++e) mx = fmaxf(mx, fmaxf(s[qb][0][e], s[qb][1][e]));
;           mx = fmaxf(mx, __shfl_xor(mx, 32));
;           const bool need = (i == 0) || (mx - mrun[qb] > 8.f);
;           if (__builtin_amdgcn_ballot_w64(need) != 0ull) {
;             const float nm = need ? mx : mrun[qb];
;             const float alpha = (i == 0) ? 1.f : ex2(mrun[qb] - nm);
;             mrun[qb] = nm; lrun[qb] *= alpha;
; #pragma unroll
;             for (int e = 0; e < 16; ++e) { o[qb][0][e] *= alpha; o[qb][1][e] *= alpha; }
;           }
;         }
;         f32x2 ps2 = {0.f, 0.f};
;         const f32x2 m2 = {mrun[qb], mrun[qb]};
; #pragma unroll
;         for (int kb = 0; kb < 2; ++kb)
; #pragma unroll
;           for (int e = 0; e < 16; e += 2) {
;             f32x2 t = {s[qb][kb][e], s[qb][kb][e + 1]};
;             if (SAFE) t = t - m2;
;             t.x = ex2(t.x); t.y = ex2(t.y);
;             ps2 += t;
;             s[qb][kb][e] = t.x; s[qb][kb][e + 1] = t.y;
;           }
;         lrun[qb] += ps2.x + ps2.y;
;         if (!SAFE) wbad = wbad || !(ps2.x + ps2.y < 1.2089258e24f);
;       }
; #pragma unroll
;       for (int kb = 0; kb < 2; ++kb)
; #pragma unroll
;         for (int t = 0; t < 2; ++t) {
;           const int kofs = 32 * kb + 16 * t + 4 * hh;
;           u32x4 va, vb2;
;           { const u32x2 lo = *(const LAS u32x2*)(vb_ + (r * VROW + kofs) * 2), hi = *(const LAS u32x2*)(vb_ + (r * VROW + kofs + 8) * 2); va.x = lo.x; va.y = lo.y; va.z = hi.x; va.w = hi.y; }
.LBB0_1258:
	s_bitcmp1_b32 s51, 0
	s_cselect_b32 s28, 0x5800, 0
	s_add_i32 s28, s28, 0
	v_add_u32_e32 v186, s28, v179
	ds_read_b128 v[64:67], v186
	ds_read_b128 v[206:209], v186 offset:32
	ds_read_b128 v[68:71], v186 offset:6656
	ds_read_b128 v[210:213], v186 offset:6688
	s_mov_b32 s51, s50
	s_waitcnt lgkmcnt(0)
	v_mfma_f32_32x32x16_bf16 v[112:127], v[64:67], v[164:167], 0
	v_mfma_f32_32x32x16_bf16 v[96:111], v[68:71], v[164:167], 0
	v_mfma_f32_32x32x16_bf16 v[80:95], v[64:67], v[172:175], 0
	v_mfma_f32_32x32x16_bf16 v[64:79], v[68:71], v[172:175], 0
	v_mfma_f32_32x32x16_bf16 v[112:127], v[206:209], v[160:163], v[112:127]
	v_mfma_f32_32x32x16_bf16 v[96:111], v[210:213], v[160:163], v[96:111]
	v_mfma_f32_32x32x16_bf16 v[80:95], v[206:209], v[168:171], v[80:95]
	v_mfma_f32_32x32x16_bf16 v[64:79], v[210:213], v[168:171], v[64:79]
	ds_read_b128 v[206:209], v186 offset:64
	ds_read_b128 v[210:213], v186 offset:96
	ds_read_b128 v[214:217], v186 offset:6720
	ds_read_b128 v[218:221], v186 offset:6752
	s_waitcnt lgkmcnt(0)
	v_mfma_f32_32x32x16_bf16 v[112:127], v[206:209], v[152:155], v[112:127]
	v_mfma_f32_32x32x16_bf16 v[112:127], v[210:213], v[148:151], v[112:127]
	v_mfma_f32_32x32x16_bf16 v[96:111], v[214:217], v[152:155], v[96:111]
	v_mfma_f32_32x32x16_bf16 v[80:95], v[206:209], v[156:159], v[80:95]
	v_mfma_f32_32x32x16_bf16 v[64:79], v[214:217], v[156:159], v[64:79]
	ds_read_b128 v[206:209], v186 offset:128
	ds_read_b128 v[214:217], v186 offset:160
	ds_read_b128 v[222:225], v186 offset:6784
	ds_read_b128 v[226:229], v186 offset:6816
	s_waitcnt lgkmcnt(0)
	v_mfma_f32_32x32x16_bf16 v[112:127], v[206:209], v[144:147], v[112:127]
	v_mfma_f32_32x32x16_bf16 v[96:111], v[218:221], v[148:151], v[96:111]
	v_mfma_f32_32x32x16_bf16 v[112:127], v[214:217], v[140:143], v[112:127]
	v_mfma_f32_32x32x16_bf16 v[96:111], v[222:225], v[144:147], v[96:111]
	s_nop 10
	v_exp_f32_e32 v230, v112
	v_exp_f32_e32 v231, v113
	v_exp_f32_e32 v232, v114
	v_exp_f32_e32 v233, v115
	v_exp_f32_e32 v234, v116
	v_exp_f32_e32 v235, v117
	v_exp_f32_e32 v236, v118
	v_mfma_f32_32x32x16_bf16 v[80:95], v[210:213], v[136:139], v[80:95]
	v_exp_f32_e32 v237, v119
	v_add_f32_e32 v112, 0, v230
	v_add_f32_e32 v113, 0, v231
	v_exp_f32_e32 v238, v120
	v_exp_f32_e32 v239, v121
	v_add_f32_e32 v112, v232, v112
	v_add_f32_e32 v113, v233, v113
	v_exp_f32_e32 v240, v122
	v_exp_f32_e32 v241, v123
	v_mfma_f32_32x32x16_bf16 v[96:111], v[226:229], v[140:143], v[96:111]
	v_add_f32_e64 v112, v234, v112
	v_add_f32_e64 v113, v235, v113
	v_exp_f32_e32 v124, v124
	v_exp_f32_e32 v125, v125
	v_add_f32_e32 v112, v236, v112
	v_add_f32_e32 v113, v237, v113
	v_exp_f32_e32 v126, v126
	v_add_f32_e32 v112, v238, v112
	v_add_f32_e32 v113, v239, v113
	v_exp_f32_e32 v127, v127
	v_mfma_f32_32x32x16_bf16 v[80:95], v[206:209], v[132:135], v[80:95]
	v_add_f32_e64 v112, v240, v112
	v_add_f32_e64 v113, v241, v113
	s_nop 0
	v_exp_f32_e32 v114, v98
	v_add_f32_e32 v118, v124, v112
	v_add_f32_e32 v119, v125, v113
	v_exp_f32_e32 v112, v96
	v_exp_f32_e32 v113, v97
	v_exp_f32_e32 v115, v99
	v_exp_f32_e32 v116, v100
	v_exp_f32_e32 v117, v101
	v_add_f32_e32 v96, v126, v118
	v_add_f32_e32 v97, v127, v119
	v_mfma_f32_32x32x16_bf16 v[80:95], v[214:217], v[128:131], v[80:95]
	v_add_f32_e64 v96, v112, v96
	v_add_f32_e64 v97, v113, v97
	v_exp_f32_e32 v118, v102
	v_add_f32_e32 v96, v114, v96
	v_add_f32_e32 v97, v115, v97
	v_exp_f32_e32 v119, v103
	v_add_f32_e32 v120, v116, v96
	v_add_f32_e32 v121, v117, v97
	v_exp_f32_e32 v96, v104
	v_exp_f32_e32 v97, v105
	v_mfma_f32_32x32x16_bf16 v[64:79], v[218:221], v[136:139], v[64:79]
	v_exp_f32_e32 v98, v106
	v_exp_f32_e32 v99, v107
	v_exp_f32_e32 v100, v108
	v_exp_f32_e32 v101, v109
	v_add_f32_e32 v102, v118, v120
	v_add_f32_e32 v103, v119, v121
	v_exp_f32_e32 v206, v82
	v_add_f32_e32 v102, v96, v102
	v_add_f32_e32 v103, v97, v103
	v_exp_f32_e32 v207, v83
	v_add_f32_e32 v102, v98, v102
	v_add_f32_e32 v103, v99, v103
	v_mfma_f32_32x32x16_bf16 v[64:79], v[222:225], v[132:135], v[64:79]
	v_add_f32_e64 v104, v100, v102
	v_add_f32_e64 v105, v101, v103
	v_exp_f32_e32 v102, v110
	v_exp_f32_e32 v103, v111
	v_exp_f32_e32 v110, v80
	v_exp_f32_e32 v111, v81
	v_exp_f32_e32 v208, v84
	v_exp_f32_e32 v209, v85
	v_exp_f32_e32 v210, v86
	v_add_f32_e32 v80, 0, v110
	v_add_f32_e32 v81, 0, v111
	v_add_u32_e32 v86, s28, v249
	v_add_f32_e32 v80, v206, v80
	v_add_f32_e32 v81, v207, v81
	v_add_f32_e32 v84, v208, v80
	v_add_f32_e32 v85, v209, v81
	v_add_u32_e32 v80, s28, v248
	ds_read2_b64 v[80:83], v80 offset0:128 offset1:130
	ds_read2_b64 v[106:109], v86 offset0:128 offset1:130
	v_mfma_f32_32x32x16_bf16 v[64:79], v[226:229], v[128:131], v[64:79]
	v_exp_f32_e32 v211, v87
	v_exp_f32_e32 v212, v88
	v_exp_f32_e32 v213, v89
	v_exp_f32_e32 v214, v90
	v_exp_f32_e32 v215, v91
	v_add_f32_e32 v84, v210, v84
	v_add_f32_e32 v85, v211, v85
	v_cvt_pk_bf16_f32 v120, v230, v231
	v_cvt_pk_bf16_f32 v121, v232, v233
	v_cvt_pk_bf16_f32 v122, v234, v235
	v_cvt_pk_bf16_f32 v123, v236, v237
	v_add_f32_e32 v84, v212, v84
	v_add_f32_e32 v85, v213, v85
	v_cvt_pk_bf16_f32 v86, v208, v209
	s_waitcnt lgkmcnt(0)
; __device__ __forceinline__ unsigned pk2(float lo, float hi) { f32x2 v = {lo, hi}; return __builtin_bit_cast(unsigned, __builtin_convertvector(v, bf16v2)); }
; #define LAS __attribute__((address_space(3)))
; __device__ __forceinline__ float ex2(float x) { return __builtin_amdgcn_exp2f(x); }
; template <bool SAFE>
; __device__ void phase_attn(const Params& p, const bf16_t* Qall, const bf16_t* Kall, const bf16_t* Vt, bf16_t* CAT, LAS unsigned char* lds) {
;     ...
;         f32x2 ps2 = {0.f, 0.f};
;         const f32x2 m2 = {mrun[qb], mrun[qb]};
; #pragma unroll
;         for (int kb = 0; kb < 2; ++kb)
; #pragma unroll
;           for (int e = 0; e < 16; e += 2) {
;             f32x2 t = {s[qb][kb][e], s[qb][kb][e + 1]};
;             if (SAFE) t = t - m2;
;             t.x = ex2(t.x); t.y = ex2(t.y);
;             ps2 += t;
;             s[qb][kb][e] = t.x; s[qb][kb][e + 1] = t.y;
;           }
;         lrun[qb] += ps2.x + ps2.y;
;         if (!SAFE) wbad = wbad || !(ps2.x + ps2.y < 1.2089258e24f);
;       }
; #pragma unroll
;       for (int kb = 0; kb < 2; ++kb)
; #pragma unroll
;         for (int t = 0; t < 2; ++t) {
;           const int kofs = 32 * kb + 16 * t + 4 * hh;
;           u32x4 va, vb2;
;           { const u32x2 lo = *(const LAS u32x2*)(vb_ + (r * VROW + kofs) * 2), hi = *(const LAS u32x2*)(vb_ + (r * VROW + kofs + 8) * 2); va.x = lo.x; va.y = lo.y; va.z = hi.x; va.w = hi.y; }
;           { const u32x2 lo = *(const LAS u32x2*)(vb_ + ((32 + r) * VROW + kofs) * 2), hi = *(const LAS u32x2*)(vb_ + ((32 + r) * VROW + kofs + 8) * 2); vb2.x = lo.x; vb2.y = lo.y; vb2.z = hi.x; vb2.w = hi.y; }
; #pragma unroll
;           for (int qb = 0; qb < 2; ++qb) {
;             u32x4 pw;
;             pw.x = pk2(s[qb][kb][8 * t], s[qb][kb][8 * t + 1]); pw.y = pk2(s[qb][kb][8 * t + 2], s[qb][kb][8 * t + 3]);
;             pw.z = pk2(s[qb][kb][8 * t + 4], s[qb][kb][8 * t + 5]); pw.w = pk2(s[qb][kb][8 * t + 6], s[qb][kb][8 * t + 7]);
;             const bf16x8 pf = __builtin_bit_cast(bf16x8, pw);
;             o[qb][0] = __builtin_amdgcn_mfma_f32_32x32x16_bf16(__builtin_bit_cast(bf16x8, va), pf, o[qb][0], 0, 0, 0);
;             o[qb][1] = __builtin_amdgcn_mfma_f32_32x32x16_bf16(__builtin_bit_cast(bf16x8, vb2), pf, o[qb][1], 0, 0, 0);
;           }
;         }
;       asm volatile("s_waitcnt vmcnt(0)" ::: "memory");
;       __syncthreads();
	v_mfma_f32_32x32x16_bf16 v[48:63], v[80:83], v[120:123], v[48:63]
	v_cvt_pk_bf16_f32 v87, v210, v211
	v_exp_f32_e32 v92, v92
	v_exp_f32_e32 v93, v93
	v_exp_f32_e32 v94, v94
	v_exp_f32_e32 v95, v95
	v_cvt_pk_bf16_f32 v88, v238, v239
	v_cvt_pk_bf16_f32 v89, v240, v241
	v_mfma_f32_32x32x16_bf16 v[32:47], v[106:109], v[120:123], v[32:47]
	v_add_f32_e64 v120, v214, v84
	v_add_f32_e64 v121, v215, v85
	v_cvt_pk_bf16_f32 v84, v110, v111
	v_exp_f32_e32 v110, v64
	v_add_u32_e32 v64, s28, v250
	v_cvt_pk_bf16_f32 v85, v206, v207
	v_exp_f32_e32 v111, v65
	v_mfma_f32_32x32x16_bf16 v[16:31], v[80:83], v[84:87], v[16:31]
	ds_read2_b64 v[80:83], v64 offset0:128 offset1:130
	v_add_u32_e32 v64, s28, v251
	v_cvt_pk_bf16_f32 v90, v124, v125
	v_cvt_pk_bf16_f32 v91, v126, v127
	v_add_f32_e32 v104, v102, v104
	v_add_f32_e32 v105, v103, v105
	v_mfma_f32_32x32x16_bf16 v[0:15], v[106:109], v[84:87], v[0:15]
	ds_read2_b64 v[84:87], v64 offset0:128 offset1:130
	v_exp_f32_e32 v106, v66
	v_exp_f32_e32 v107, v67
	v_add_f32_e32 v64, v92, v120
	v_add_f32_e32 v65, v93, v121
	v_exp_f32_e32 v120, v68
	v_exp_f32_e32 v121, v69
	v_add_f32_e32 v64, v94, v64
	v_add_f32_e32 v65, v95, v65
	s_waitcnt lgkmcnt(0)
	v_mfma_f32_32x32x16_bf16 v[48:63], v[80:83], v[88:91], v[48:63]
	v_add_f32_e64 v64, v110, v64
	v_add_f32_e64 v65, v111, v65
	v_cvt_pk_bf16_f32 v66, v92, v93
	v_add_f32_e64 v108, v106, v64
	v_add_f32_e64 v109, v107, v65
	v_cvt_pk_bf16_f32 v64, v212, v213
	v_add_f32_e32 v68, v120, v108
	v_add_f32_e32 v69, v121, v109
	v_cvt_pk_bf16_f32 v65, v214, v215
	v_cvt_pk_bf16_f32 v67, v94, v95
	v_mfma_f32_32x32x16_bf16 v[32:47], v[84:87], v[88:91], v[32:47]
	v_exp_f32_e32 v88, v70
	v_exp_f32_e32 v89, v71
	v_exp_f32_e32 v92, v72
	v_exp_f32_e32 v93, v73
	v_add_f32_e32 v90, v88, v68
	v_add_f32_e32 v91, v89, v69
	v_add_u32_e32 v68, s28, v252
	v_mfma_f32_32x32x16_bf16 v[16:31], v[80:83], v[64:67], v[16:31]
	ds_read2_b64 v[68:71], v68 offset0:128 offset1:130
	v_add_f32_e64 v72, v92, v90
	v_add_f32_e64 v73, v93, v91
	v_exp_f32_e32 v90, v78
	v_exp_f32_e32 v91, v79
	v_cvt_pk_bf16_f32 v80, v112, v113
	v_cvt_pk_bf16_f32 v81, v114, v115
	v_mfma_f32_32x32x16_bf16 v[0:15], v[84:87], v[64:67], v[0:15]
	v_add_u32_e32 v64, s28, v253
	ds_read2_b64 v[64:67], v64 offset0:128 offset1:130
	v_exp_f32_e32 v84, v74
	v_exp_f32_e32 v85, v75
	v_exp_f32_e32 v86, v76
	v_exp_f32_e32 v87, v77
	v_cvt_pk_bf16_f32 v82, v116, v117
	v_add_f32_e32 v72, v84, v72
	v_add_f32_e32 v73, v85, v73
	v_cvt_pk_bf16_f32 v83, v118, v119
	v_add_f32_e32 v72, v86, v72
	v_add_f32_e32 v73, v87, v73
	v_cvt_pk_bf16_f32 v74, v120, v121
	v_add_f32_e32 v76, v90, v72
	v_add_f32_e32 v77, v91, v73
	v_cvt_pk_bf16_f32 v72, v110, v111
	v_cvt_pk_bf16_f32 v73, v106, v107
	v_cvt_pk_bf16_f32 v75, v88, v89
	s_waitcnt lgkmcnt(0)
	v_mfma_f32_32x32x16_bf16 v[48:63], v[68:71], v[80:83], v[48:63]
	v_cvt_pk_bf16_f32 v78, v86, v87
	v_cvt_pk_bf16_f32 v79, v90, v91
	v_mfma_f32_32x32x16_bf16 v[16:31], v[68:71], v[72:75], v[16:31]
	v_add_f32_e32 v76, v76, v77
	v_add_f32_e32 v77, v104, v105
	v_add_u32_e32 v68, s28, v254
	ds_read2_b64 v[68:71], v68 offset0:128 offset1:130
	v_mfma_f32_32x32x16_bf16 v[32:47], v[64:67], v[80:83], v[32:47]
	v_cmp_ngt_f32_e32 vcc, s44, v77
	v_add_f32_e64 v194, v194, v76
	v_add_f32_e64 v195, v195, v77
	v_cvt_pk_bf16_f32 v77, v84, v85
	v_mfma_f32_32x32x16_bf16 v[0:15], v[64:67], v[72:75], v[0:15]
	v_add_u32_e32 v64, s28, v255
	ds_read2_b64 v[64:67], v64 offset0:128 offset1:130
	v_cvt_pk_bf16_f32 v72, v96, v97
	v_cvt_pk_bf16_f32 v73, v98, v99
	v_cvt_pk_bf16_f32 v74, v100, v101
	v_cvt_pk_bf16_f32 v75, v102, v103
	s_or_b64 s[28:29], s[26:27], vcc
	v_cmp_ngt_f32_e32 vcc, s44, v76
	v_cvt_pk_bf16_f32 v76, v92, v93
	s_waitcnt lgkmcnt(0)
	v_mfma_f32_32x32x16_bf16 v[48:63], v[68:71], v[72:75], v[48:63]
	s_or_b64 s[28:29], s[28:29], vcc
	s_add_u32 s4, s4, 0x3000
	s_addc_u32 s5, s5, 0
	s_add_u32 s15, s15, 0x80
	s_waitcnt vmcnt(0)
	s_addc_u32 s49, s49, 0
	s_andn2_b64 s[26:27], s[26:27], exec
	v_mfma_f32_32x32x16_bf16 v[32:47], v[64:67], v[72:75], v[32:47]
	s_and_b64 s[52:53], s[28:29], exec
	s_or_b64 s[26:27], s[26:27], s[52:53]
	s_cmp_eq_u32 s1, s50
	s_waitcnt vmcnt(0)
	s_barrier
	v_mfma_f32_32x32x16_bf16 v[16:31], v[68:71], v[76:79], v[16:31]
	v_mfma_f32_32x32x16_bf16 v[0:15], v[64:67], v[76:79], v[0:15]
	s_cbranch_scc1 .LBB0_1261
.LBB0_1259:
	s_add_i32 s50, s51, 1
	s_bitcmp1_b32 s50, 0
	s_cselect_b32 s0, 0x5800, 0
	s_add_i32 s0, s0, 0
	s_and_b64 s[28:29], s[10:11], exec
	s_cselect_b32 s29, s5, s49
	s_cselect_b32 s28, s4, s15
	s_add_i32 m0, s0, s34
	s_and_b64 vcc, exec, s[8:9]
	global_load_lds_dwordx4 v182, s[28:29]
	s_cbranch_vccnz .LBB0_1258
	s_add_i32 s52, s0, s36
	s_and_b64 s[28:29], exec, s[16:17]
	s_cselect_b32 s29, s5, s49
	s_cselect_b32 s28, s4, s15
	s_add_i32 m0, s0, s35
	s_nop 0
	global_load_lds_dwordx4 v180, s[28:29]
	s_mov_b32 m0, s52
	s_nop 0
	global_load_lds_dwordx4 v184, s[28:29]
	s_branch .LBB0_1258

; #define LAS __attribute__((address_space(3)))
; template <bool OUT>
; __device__ void phase_hgrn(const Params& p, const bf16_t* Qh, const bf16_t* Vv, const _Float16* Lfb, bf16_t* Of, bf16_t* Ob, float* Sseg, float* Dlog, LAS unsigned char* lds) {
;     ...
;       const int rbase = (c < 4) ? b * 256 + (dir ? 255 - 64 * c : 64 * c) : NCTX + b * 8192 + (dir ? 8191 - 64 * (c - 4) : 64 * (c - 4));
;       float lf[16], cs[16];
;       float run = 0.f;
; #pragma unroll
;       for (int i = 0; i < 16; ++i) { lf[i] = (float)lfr[i]; run += lf[i]; cs[i] = run; }
;       *(LAS float*)(lds + TOT + (tq * 128 + dk) * 4) = run;
;       __syncthreads();
;       float offs = 0.f, blast = 0.f;
; #pragma unroll
;       for (int g = 0; g < 4; ++g) { const float t = *(const LAS float*)(lds + TOT + (g * 128 + dk) * 4); blast += t; if (g < tq) offs += t; }
.Lhga_keep:
	v_add_u32_e32 v228, s98, v61
	v_ashrrev_i32_e32 v229, 31, v228
	v_lshlrev_b64 v[228:229], 11, v[228:229]
	v_lshl_or_b32 v228, v52, 1, v228
	v_cvt_f32_f16_e32 v54, v62
	v_cvt_f32_f16_e32 v83, v63
	v_cvt_f32_f16_e32 v84, v64
	v_cvt_f32_f16_e32 v85, v65
	v_add_f32_e32 v82, 0, v54
	v_cvt_f32_f16_e32 v89, v66
	v_add_f32_e32 v86, v82, v83
	v_cvt_f32_f16_e32 v90, v67
	v_add_f32_e32 v87, v86, v84
	v_cvt_f32_f16_e32 v91, v68
	v_add_f32_e32 v88, v87, v85
	v_cvt_f32_f16_e32 v92, v69
	v_add_f32_e32 v93, v88, v89
	v_cvt_f32_f16_e32 v97, v70
	v_add_f32_e32 v94, v93, v90
	v_cvt_f32_f16_e32 v98, v71
	v_add_f32_e32 v95, v94, v91
	v_cvt_f32_f16_e32 v99, v72
	v_add_f32_e32 v96, v95, v92
	v_cvt_f32_f16_e32 v100, v73
	v_add_f32_e32 v101, v96, v97
	v_cvt_f32_f16_e32 v105, v74
	v_add_f32_e32 v102, v101, v98
	v_cvt_f32_f16_e32 v106, v75
	v_add_f32_e32 v103, v102, v99
	v_cvt_f32_f16_e32 v107, v76
	v_add_f32_e32 v104, v103, v100
	s_waitcnt vmcnt(0)
	v_cvt_f32_f16_e32 v108, v77
	v_add_f32_e32 v109, v104, v105
	v_add_f32_e32 v110, v109, v106
	v_add_f32_e32 v111, v110, v107
	v_add_f32_e32 v112, v111, v108
	v_add_u32_e32 v80, s60, v44
	ds_write_b32 v59, v112
	s_waitcnt lgkmcnt(0)
	s_barrier
; #define LAS __attribute__((address_space(3)))
; template <bool OUT>
; __device__ void phase_hgrn(const Params& p, const bf16_t* Qh, const bf16_t* Vv, const _Float16* Lfb, bf16_t* Of, bf16_t* Ob, float* Sseg, float* Dlog, LAS unsigned char* lds) {
;     ...
;       float offs = 0.f, blast = 0.f;
; #pragma unroll
;       for (int g = 0; g < 4; ++g) { const float t = *(const LAS float*)(lds + TOT + (g * 128 + dk) * 4); blast += t; if (g < tq) offs += t; }
;       {
;         const float eblast = __expf(blast);
;         unsigned kew[8], vw[8];
; #pragma unroll
;         for (int i = 0; i < 16; i += 2) {
;           float qt[2], kt[2], ke[2];
; #pragma unroll
;           for (int e = 0; e < 2; ++e) {
;             const float bb = offs + cs[i + e];
;             const float k = 1.f - __expf(lf[i + e]);
;             const float ken = k * __expf(-bb);
;             if constexpr (OUT) { qt[e] = bf2f(qr[i + e]) * __expf(bb); kt[e] = ken; }
;             ke[e] = ken * eblast;
;           }
;           if constexpr (OUT) {
;             const unsigned qp = pk2(qt[0], qt[1]), kp = pk2(kt[0], kt[1]);
;             const int s = 16 * tq + i;
;             *(LAS bf16_t*)(lds + QT + (s * 136 + dk) * 2) = (bf16_t)(qp & 0xffffu);
;             *(LAS bf16_t*)(lds + QT + ((s + 1) * 136 + dk) * 2) = (bf16_t)(qp >> 16);
;             *(LAS bf16_t*)(lds + KT + (s * 136 + dk) * 2) = (bf16_t)(kp & 0xffffu);
;             *(LAS bf16_t*)(lds + KT + ((s + 1) * 136 + dk) * 2) = (bf16_t)(kp >> 16);
;           }
;           kew[i >> 1] = pk2(ke[0], ke[1]);
;           vw[i >> 1] = (unsigned)vr[i] | ((unsigned)vr[i + 1] << 16);
;         }
;         *(LAS u32x4*)(lds + KE + (dk * 72 + 16 * tq) * 2) = (u32x4){kew[0], kew[1], kew[2], kew[3]};
;         *(LAS u32x4*)(lds + KE + (dk * 72 + 16 * tq + 8) * 2) = (u32x4){kew[4], kew[5], kew[6], kew[7]};
;         *(LAS u32x4*)(lds + VT + (dk * 72 + 16 * tq) * 2) = (u32x4){vw[0], vw[1], vw[2], vw[3]};
;         *(LAS u32x4*)(lds + VT + (dk * 72 + 16 * tq + 8) * 2) = (u32x4){vw[4], vw[5], vw[6], vw[7]};
;         if (tq == 0) *(LAS float*)(lds + DC + dk * 4) = eblast;
;         dsum += blast;
;       }
;       __syncthreads();
;       if (c + 1 < c_end) {
;         const int cn = c + 1;
;         const int rb = (cn < 4) ? b * 256 + (dir ? 255 - 64 * cn : 64 * cn) : NCTX + b * 8192 + (dir ? 8191 - 64 * (cn - 4) : 64 * (cn - 4));
	ds_read2st64_b32 v[78:79], v80 offset1:2
	ds_read2st64_b32 v[80:81], v80 offset0:4 offset1:6
	v_mul_f32_e32 v54, 0x3fb8aa3b, v54
	s_waitcnt lgkmcnt(1)
	v_add_f32_e32 v78, 0, v78
	v_cndmask_b32_e64 v113, v78, 0, s[6:7]
	global_load_ushort v180, v228, s[20:21]
	v_add_f32_e32 v78, v78, v79
	v_add_f32_e32 v79, v79, v113
	v_cndmask_b32_e64 v79, v113, v79, s[8:9]
	s_waitcnt lgkmcnt(0)
	global_load_ushort v212, v228, s[14:15]
	v_add_u32_e32 v230, s22, v228
	v_add_f32_e32 v78, v78, v80
	v_add_f32_e32 v80, v80, v79
	v_cndmask_b32_e64 v79, v79, v80, s[10:11]
	v_add_f32_e32 v80, v81, v79
	global_load_ushort v181, v230, s[20:21]
	v_cndmask_b32_e64 v79, v79, v80, s[12:13]
	v_add_f32_e32 v78, v78, v81
	v_add_f32_e32 v81, v82, v79
	v_exp_f32_e32 v80, v54
	global_load_ushort v213, v230, s[14:15]
	v_add_u32_e32 v231, s24, v228
	v_mul_f32_e32 v54, 0xbfb8aa3b, v81
	v_exp_f32_e32 v82, v54
	v_add_f32_e32 v54, v86, v79
	v_mul_f32_e32 v81, 0x3fb8aa3b, v83
	global_load_ushort v182, v231, s[20:21]
	v_exp_f32_e32 v81, v81
	v_mul_f32_e32 v54, 0xbfb8aa3b, v54
	v_exp_f32_e32 v83, v54
	v_mul_f32_e32 v54, 0x3fb8aa3b, v78
	global_load_ushort v214, v231, s[14:15]
	v_add_u32_e32 v232, s26, v228
	v_pk_add_f32 v[80:81], v[80:81], 1.0 op_sel_hi:[1,0] neg_lo:[1,0] neg_hi:[1,0]
	v_exp_f32_e32 v54, v54
	v_pk_mul_f32 v[80:81], v[80:81], v[82:83]
	v_add_f32_e32 v83, v87, v79
	global_load_ushort v183, v232, s[20:21]
	v_mul_f32_e32 v83, 0xbfb8aa3b, v83
	v_mul_f32_e32 v82, 0x3fb8aa3b, v84
	v_exp_f32_e32 v84, v83
	v_add_f32_e32 v86, v88, v79
	global_load_ushort v215, v232, s[14:15]
	v_add_u32_e32 v233, s28, v228
	v_mul_f32_e32 v83, 0x3fb8aa3b, v85
	v_exp_f32_e32 v82, v82
	v_exp_f32_e32 v83, v83
	v_mul_f32_e32 v85, 0xbfb8aa3b, v86
	global_load_ushort v184, v233, s[20:21]
	v_exp_f32_e32 v85, v85
	v_pk_mul_f32 v[80:81], v[54:55], v[80:81] op_sel_hi:[0,1]
	v_cvt_pk_bf16_f32 v80, v80, v81
	v_pk_add_f32 v[82:83], v[82:83], 1.0 op_sel_hi:[1,0] neg_lo:[1,0] neg_hi:[1,0]
	global_load_ushort v216, v233, s[14:15]
	v_add_u32_e32 v234, s30, v228
	v_add_f32_e32 v81, v93, v79
	v_pk_mul_f32 v[82:83], v[82:83], v[84:85]
	v_mul_f32_e32 v84, 0x3fb8aa3b, v89
	global_load_ushort v185, v234, s[20:21]
	v_mul_f32_e32 v81, 0xbfb8aa3b, v81
	v_mul_f32_e32 v85, 0x3fb8aa3b, v90
	v_exp_f32_e32 v84, v84
	v_exp_f32_e32 v86, v81
	global_load_ushort v217, v234, s[14:15]
	v_add_u32_e32 v235, s34, v228
	v_add_f32_e32 v81, v94, v79
	v_exp_f32_e32 v85, v85
	v_mul_f32_e32 v81, 0xbfb8aa3b, v81
	v_exp_f32_e32 v87, v81
	global_load_ushort v186, v235, s[20:21]
	v_pk_mul_f32 v[82:83], v[54:55], v[82:83] op_sel_hi:[0,1]
	v_cvt_pk_bf16_f32 v81, v82, v83
	v_pk_add_f32 v[82:83], v[84:85], 1.0 op_sel_hi:[1,0] neg_lo:[1,0] neg_hi:[1,0]
	v_add_f32_e32 v85, v95, v79
	global_load_ushort v218, v235, s[14:15]
	v_add_u32_e32 v236, s36, v228
	v_mul_f32_e32 v85, 0xbfb8aa3b, v85
	v_pk_mul_f32 v[82:83], v[82:83], v[86:87]
	v_mul_f32_e32 v84, 0x3fb8aa3b, v91
	v_exp_f32_e32 v86, v85
	global_load_ushort v187, v236, s[20:21]
	v_add_f32_e32 v87, v96, v79
	v_mul_f32_e32 v85, 0x3fb8aa3b, v92
	v_exp_f32_e32 v84, v84
	v_exp_f32_e32 v85, v85
	global_load_ushort v219, v236, s[14:15]
	v_add_u32_e32 v237, s38, v228
	v_mul_f32_e32 v87, 0xbfb8aa3b, v87
	v_exp_f32_e32 v87, v87
	v_pk_mul_f32 v[82:83], v[54:55], v[82:83] op_sel_hi:[0,1]
	v_cvt_pk_bf16_f32 v82, v82, v83
	global_load_ushort v188, v237, s[20:21]
	v_pk_add_f32 v[84:85], v[84:85], 1.0 op_sel_hi:[1,0] neg_lo:[1,0] neg_hi:[1,0]
	v_add_f32_e32 v83, v101, v79
	v_pk_mul_f32 v[84:85], v[84:85], v[86:87]
	v_mul_f32_e32 v86, 0x3fb8aa3b, v97
	global_load_ushort v220, v237, s[14:15]
	v_add_u32_e32 v230, s40, v228
	v_mul_f32_e32 v83, 0xbfb8aa3b, v83
	v_mul_f32_e32 v87, 0x3fb8aa3b, v98
	v_exp_f32_e32 v86, v86
	v_exp_f32_e32 v88, v83
	global_load_ushort v189, v230, s[20:21]
	v_add_f32_e32 v83, v102, v79
	v_exp_f32_e32 v87, v87
	v_mul_f32_e32 v83, 0xbfb8aa3b, v83
	v_exp_f32_e32 v89, v83
	global_load_ushort v221, v230, s[14:15]
	v_add_u32_e32 v231, s42, v228
	v_pk_mul_f32 v[84:85], v[54:55], v[84:85] op_sel_hi:[0,1]
	v_cvt_pk_bf16_f32 v83, v84, v85
	v_pk_add_f32 v[84:85], v[86:87], 1.0 op_sel_hi:[1,0] neg_lo:[1,0] neg_hi:[1,0]
	v_add_f32_e32 v87, v103, v79
	global_load_ushort v190, v231, s[20:21]
	v_mul_f32_e32 v87, 0xbfb8aa3b, v87
	v_pk_mul_f32 v[84:85], v[84:85], v[88:89]
	v_mul_f32_e32 v86, 0x3fb8aa3b, v99
	global_load_ushort v222, v231, s[14:15]
	v_add_u32_e32 v232, s44, v228
	v_exp_f32_e32 v88, v87
	v_add_f32_e32 v89, v104, v79
	v_mul_f32_e32 v87, 0x3fb8aa3b, v100
	v_exp_f32_e32 v86, v86
	global_load_ushort v191, v232, s[20:21]
	v_exp_f32_e32 v87, v87
	v_mul_f32_e32 v89, 0xbfb8aa3b, v89
	v_exp_f32_e32 v89, v89
	v_pk_mul_f32 v[84:85], v[54:55], v[84:85] op_sel_hi:[0,1]
	global_load_ushort v223, v232, s[14:15]
	v_add_u32_e32 v233, s46, v228
	v_cvt_pk_bf16_f32 v84, v84, v85
	v_pk_add_f32 v[86:87], v[86:87], 1.0 op_sel_hi:[1,0] neg_lo:[1,0] neg_hi:[1,0]
	v_add_f32_e32 v85, v109, v79
	v_pk_mul_f32 v[86:87], v[86:87], v[88:89]
	global_load_ushort v192, v233, s[20:21]
	v_mul_f32_e32 v88, 0x3fb8aa3b, v105
	v_mul_f32_e32 v85, 0xbfb8aa3b, v85
	v_mul_f32_e32 v89, 0x3fb8aa3b, v106
	v_exp_f32_e32 v88, v88
	global_load_ushort v224, v233, s[14:15]
	v_add_u32_e32 v234, s48, v228
	v_exp_f32_e32 v90, v85
	v_add_f32_e32 v85, v110, v79
	v_exp_f32_e32 v89, v89
	v_mul_f32_e32 v85, 0xbfb8aa3b, v85
	global_load_ushort v193, v234, s[20:21]
	v_exp_f32_e32 v91, v85
	v_pk_mul_f32 v[86:87], v[54:55], v[86:87] op_sel_hi:[0,1]
	v_cvt_pk_bf16_f32 v85, v86, v87
	v_pk_add_f32 v[86:87], v[88:89], 1.0 op_sel_hi:[1,0] neg_lo:[1,0] neg_hi:[1,0]
	global_load_ushort v225, v234, s[14:15]
	v_add_u32_e32 v235, s50, v228
	v_add_f32_e32 v89, v111, v79
	v_mul_f32_e32 v89, 0xbfb8aa3b, v89
	v_pk_mul_f32 v[86:87], v[86:87], v[90:91]
	v_mul_f32_e32 v88, 0x3fb8aa3b, v107
	global_load_ushort v194, v235, s[20:21]
	v_exp_f32_e32 v90, v89
	v_add_f32_e32 v79, v112, v79
	v_mul_f32_e32 v89, 0x3fb8aa3b, v108
	v_exp_f32_e32 v88, v88
	global_load_ushort v226, v235, s[14:15]
	v_add_u32_e32 v236, s52, v228
	v_exp_f32_e32 v89, v89
	v_mul_f32_e32 v79, 0xbfb8aa3b, v79
	v_exp_f32_e32 v91, v79
	v_pk_mul_f32 v[86:87], v[54:55], v[86:87] op_sel_hi:[0,1]
	global_load_ushort v195, v236, s[20:21]
	v_pk_add_f32 v[88:89], v[88:89], 1.0 op_sel_hi:[1,0] neg_lo:[1,0] neg_hi:[1,0]
	v_cvt_pk_bf16_f32 v86, v86, v87
	v_pk_mul_f32 v[88:89], v[88:89], v[90:91]
	s_nop 0
	global_load_ushort v227, v236, s[14:15]
	v_pk_mul_f32 v[88:89], v[54:55], v[88:89] op_sel_hi:[0,1]
	v_cvt_pk_bf16_f32 v87, v88, v89
	ds_write_b128 v55, v[80:83] offset:34816
	ds_write_b128 v55, v[84:87] offset:34832
	ds_write_b128 v55, v[32:35] offset:53248
	ds_write_b128 v55, v[36:39] offset:53264
	s_and_saveexec_b64 s[0:1], s[6:7]
	v_add_u32_e32 v79, 0, v53
	v_add_u32_e32 v79, 0x1c400, v79
	ds_write_b32 v79, v54
	s_or_b64 exec, exec, s[0:1]
	s_add_i32 s4, s63, 1
	s_cmp_ge_i32 s4, s62
	s_waitcnt lgkmcnt(0)
	s_barrier

; template <bool OUT>
; __device__ void phase_hgrn(const Params& p, const bf16_t* Qh, const bf16_t* Vv, const _Float16* Lfb, bf16_t* Of, bf16_t* Ob, float* Sseg, float* Dlog, LAS unsigned char* lds) {
;     ...
;         const int cn = c + 1;
;         const int rb = (cn < 4) ? b * 256 + (dir ? 255 - 64 * cn : 64 * cn) : NCTX + b * 8192 + (dir ? 8191 - 64 * (cn - 4) : 64 * (cn - 4));
;         const size_t o0 = (size_t)(rb + sgn * 16 * tq) * DM + h * 128 + dk;
; #pragma unroll
;         for (int i = 0; i < 16; ++i) { const size_t o = o0 + (ptrdiff_t)(sgn * i) * DM; lfr[i] = Lx[o]; if constexpr (OUT) qr[i] = Qh[o]; else qr[i] = 0; vr[i] = Vv[o]; }
.Lhgc_keep:
	v_add_u32_e32 v228, s98, v117
	v_ashrrev_i32_e32 v229, 31, v228
	v_lshlrev_b64 v[228:229], 11, v[228:229]
	v_lshl_or_b32 v228, v78, 1, v228
	s_add_i32 s5, s29, s2
	s_cmp_gt_u32 s34, 3
	s_mov_b64 s[0:1], -1
	s_cbranch_scc0 .LBB0_2290
	s_add_i32 s3, s30, 64
	s_add_i32 s4, s5, 0xffffff00
	s_and_b64 s[0:1], s[50:51], exec
	s_cselect_b32 s0, s4, s3
	s_add_i32 s3, s0, s27
	s_mov_b64 s[0:1], 0

; #define LAS __attribute__((address_space(3)))
; template <bool OUT>
; __device__ void phase_hgrn(const Params& p, const bf16_t* Qh, const bf16_t* Vv, const _Float16* Lfb, bf16_t* Of, bf16_t* Ob, float* Sseg, float* Dlog, LAS unsigned char* lds) {
;     ...
;     for (int c = c_begin; c < c_end; ++c) {
;       const int rbase = (c < 4) ? b * 256 + (dir ? 255 - 64 * c : 64 * c) : NCTX + b * 8192 + (dir ? 8191 - 64 * (c - 4) : 64 * (c - 4));
;       float lf[16], cs[16];
;       float run = 0.f;
; #pragma unroll
;       for (int i = 0; i < 16; ++i) { lf[i] = (float)lfr[i]; run += lf[i]; cs[i] = run; }
;       *(LAS float*)(lds + TOT + (tq * 128 + dk) * 4) = run;
;       __syncthreads();
;       float offs = 0.f, blast = 0.f;
; #pragma unroll
;       for (int g = 0; g < 4; ++g) { const float t = *(const LAS float*)(lds + TOT + (g * 128 + dk) * 4); blast += t; if (g < tq) offs += t; }
;       {
;         const float eblast = __expf(blast);
;         unsigned kew[8], vw[8];
; #pragma unroll
;         for (int i = 0; i < 16; i += 2) {
;           float qt[2], kt[2], ke[2];
; #pragma unroll
;           for (int e = 0; e < 2; ++e) {
;             const float bb = offs + cs[i + e];
;             const float k = 1.f - __expf(lf[i + e]);
;             const float ken = k * __expf(-bb);
;             if constexpr (OUT) { qt[e] = bf2f(qr[i + e]) * __expf(bb); kt[e] = ken; }
;             ke[e] = ken * eblast;
;           }
;           if constexpr (OUT) {
;             const unsigned qp = pk2(qt[0], qt[1]), kp = pk2(kt[0], kt[1]);
;             const int s = 16 * tq + i;
;             *(LAS bf16_t*)(lds + QT + (s * 136 + dk) * 2) = (bf16_t)(qp & 0xffffu);
;             *(LAS bf16_t*)(lds + QT + ((s + 1) * 136 + dk) * 2) = (bf16_t)(qp >> 16);
;             *(LAS bf16_t*)(lds + KT + (s * 136 + dk) * 2) = (bf16_t)(kp & 0xffffu);
;             *(LAS bf16_t*)(lds + KT + ((s + 1) * 136 + dk) * 2) = (bf16_t)(kp >> 16);
;           }
;           kew[i >> 1] = pk2(ke[0], ke[1]);
;           vw[i >> 1] = (unsigned)vr[i] | ((unsigned)vr[i + 1] << 16);
;         }
;         *(LAS u32x4*)(lds + KE + (dk * 72 + 16 * tq) * 2) = (u32x4){kew[0], kew[1], kew[2], kew[3]};
;         *(LAS u32x4*)(lds + KE + (dk * 72 + 16 * tq + 8) * 2) = (u32x4){kew[4], kew[5], kew[6], kew[7]};
;         *(LAS u32x4*)(lds + VT + (dk * 72 + 16 * tq) * 2) = (u32x4){vw[0], vw[1], vw[2], vw[3]};
.LBB0_2292:
	v_cvt_f32_f16_e32 v37, v118
	v_cvt_f32_f16_e32 v39, v119
	v_cvt_f32_f16_e32 v40, v120
	v_cvt_f32_f16_e32 v41, v121
	v_add_f32_e32 v38, 0, v37
	v_cvt_f32_f16_e32 v45, v122
	v_add_f32_e32 v42, v38, v39
	v_cvt_f32_f16_e32 v46, v123
	v_add_f32_e32 v43, v42, v40
	v_cvt_f32_f16_e32 v47, v115
	v_add_f32_e32 v44, v43, v41
	v_cvt_f32_f16_e32 v56, v116
	v_add_f32_e32 v57, v44, v45
	v_cvt_f32_f16_e32 v61, v125
	v_add_f32_e32 v58, v57, v46
	v_cvt_f32_f16_e32 v62, v126
	v_add_f32_e32 v59, v58, v47
	v_cvt_f32_f16_e32 v63, v127
	v_add_f32_e32 v60, v59, v56
	v_cvt_f32_f16_e32 v140, v130
	v_add_f32_e32 v141, v60, v61
	v_cvt_f32_f16_e32 v145, v131
	v_add_f32_e32 v142, v141, v62
	v_cvt_f32_f16_e32 v146, v132
	v_add_f32_e32 v143, v142, v63
	v_cvt_f32_f16_e32 v147, v128
	v_add_f32_e32 v144, v143, v140
	v_cvt_f32_f16_e32 v148, v129
	v_add_f32_e32 v149, v144, v145
	v_add_f32_e32 v150, v149, v146
	v_add_f32_e32 v151, v150, v147
	v_add_f32_e32 v152, v151, v148
	v_add_u32_e32 v32, s25, v79
	ds_write_b32 v32, v152
	s_waitcnt lgkmcnt(0)
	s_barrier
	ds_read2st64_b32 v[32:33], v84 offset1:2
	ds_read2st64_b32 v[34:35], v84 offset0:4 offset1:6
	s_waitcnt lgkmcnt(1)
	v_add_f32_e32 v32, 0, v32
	v_cndmask_b32_e64 v36, v32, 0, s[6:7]
	v_add_f32_e32 v32, v32, v33
	v_add_f32_e32 v33, v33, v36
	v_cndmask_b32_e64 v33, v36, v33, s[10:11]
	s_waitcnt lgkmcnt(0)
	v_add_f32_e32 v32, v32, v34
	v_add_f32_e32 v34, v34, v33
	v_cndmask_b32_e64 v33, v33, v34, s[12:13]
	v_add_f32_e32 v34, v35, v33
	global_load_ushort v180, v228, s[64:65]
	v_cndmask_b32_e64 v153, v33, v34, s[14:15]
	v_add_f32_e32 v32, v32, v35
	v_add_f32_e32 v33, v38, v153
	v_mul_f32_e32 v32, 0x3fb8aa3b, v32
	v_mul_f32_e32 v34, 0xbfb8aa3b, v33
	global_load_ushort v196, v228, s[54:55]
	v_mul_f32_e32 v33, 0x3fb8aa3b, v33
	v_exp_f32_e32 v36, v32
	v_mul_f32_e32 v32, 0x3fb8aa3b, v37
	v_exp_f32_e32 v38, v33
	v_mul_f32_e32 v33, 0x3fb8aa3b, v39
	global_load_ushort v212, v228, s[60:61]
	v_add_u32_e32 v230, s66, v228
	v_add_f32_e32 v37, v42, v153
	v_exp_f32_e32 v32, v32
	v_exp_f32_e32 v33, v33
	v_mul_f32_e32 v35, 0xbfb8aa3b, v37
	v_exp_f32_e32 v34, v34
	global_load_ushort v181, v230, s[64:65]
	v_exp_f32_e32 v35, v35
	v_mul_f32_e32 v37, 0x3fb8aa3b, v37
	v_exp_f32_e32 v39, v37
	v_pk_add_f32 v[32:33], v[32:33], 1.0 op_sel_hi:[1,0] neg_lo:[1,0] neg_hi:[1,0]
	global_load_ushort v197, v230, s[54:55]
	s_nop 0
	v_pk_mul_f32 v[32:33], v[32:33], v[34:35]
	v_and_b32_e32 v35, 0xffff0000, v75
	v_lshlrev_b32_e32 v34, 16, v75
	v_pk_mul_f32 v[34:35], v[38:39], v[34:35]
	global_load_ushort v213, v230, s[60:61]
	v_add_u32_e32 v231, s68, v228
	v_pk_mul_f32 v[38:39], v[36:37], v[32:33] op_sel_hi:[0,1]
	v_cvt_pk_bf16_f32 v32, v32, v33
	v_add_f32_e32 v33, v43, v153
	v_cvt_pk_bf16_f32 v34, v34, v35
	v_mul_f32_e32 v35, 0xbfb8aa3b, v33
	global_load_ushort v182, v231, s[64:65]
	v_mul_f32_e32 v33, 0x3fb8aa3b, v33
	ds_write_b16 v85, v34
	ds_write_b16_d16_hi v86, v34
	ds_write_b16 v85, v32 offset:17408
	ds_write_b16_d16_hi v86, v32 offset:17408
	global_load_ushort v198, v231, s[54:55]
	v_mul_f32_e32 v34, 0x3fb8aa3b, v40
	v_exp_f32_e32 v40, v33
	v_mul_f32_e32 v33, 0x3fb8aa3b, v41
	v_cvt_pk_bf16_f32 v32, v38, v39
	v_exp_f32_e32 v38, v35
	global_load_ushort v214, v231, s[60:61]
	v_add_u32_e32 v232, s70, v228
	v_exp_f32_e32 v35, v33
	v_add_f32_e32 v33, v44, v153
	v_exp_f32_e32 v34, v34
	v_mul_f32_e32 v37, 0xbfb8aa3b, v33
	global_load_ushort v183, v232, s[64:65]
	v_exp_f32_e32 v39, v37
	v_mul_f32_e32 v33, 0x3fb8aa3b, v33
	v_exp_f32_e32 v41, v33
	v_pk_add_f32 v[34:35], v[34:35], 1.0 op_sel_hi:[1,0] neg_lo:[1,0] neg_hi:[1,0]
	s_nop 0
	global_load_ushort v199, v232, s[54:55]
	v_pk_mul_f32 v[34:35], v[34:35], v[38:39]
	v_and_b32_e32 v39, 0xffff0000, v133
	v_lshlrev_b32_e32 v38, 16, v133
	v_pk_mul_f32 v[38:39], v[40:41], v[38:39]
	v_pk_mul_f32 v[40:41], v[36:37], v[34:35] op_sel_hi:[0,1]
	global_load_ushort v215, v232, s[60:61]
	v_add_u32_e32 v233, s72, v228
	v_cvt_pk_bf16_f32 v34, v34, v35
	v_add_f32_e32 v35, v57, v153
	v_cvt_pk_bf16_f32 v33, v38, v39
	v_mul_f32_e32 v37, 0xbfb8aa3b, v35
	v_mul_f32_e32 v35, 0x3fb8aa3b, v35
	global_load_ushort v184, v233, s[64:65]
	ds_write_b16 v87, v33
	ds_write_b16_d16_hi v88, v33
	ds_write_b16 v87, v34 offset:17408
	ds_write_b16_d16_hi v88, v34 offset:17408
	v_cvt_pk_bf16_f32 v33, v40, v41
	global_load_ushort v200, v233, s[54:55]
	v_mul_f32_e32 v34, 0x3fb8aa3b, v45
	v_exp_f32_e32 v38, v37
	v_exp_f32_e32 v40, v35
	v_mul_f32_e32 v35, 0x3fb8aa3b, v46
	global_load_ushort v216, v233, s[60:61]
	v_add_u32_e32 v234, s74, v228
	v_add_f32_e32 v37, v58, v153
	v_exp_f32_e32 v34, v34
	v_exp_f32_e32 v35, v35
	v_mul_f32_e32 v39, 0xbfb8aa3b, v37
	v_exp_f32_e32 v39, v39
	global_load_ushort v185, v234, s[64:65]
	v_mul_f32_e32 v37, 0x3fb8aa3b, v37
	v_exp_f32_e32 v41, v37
	v_pk_add_f32 v[34:35], v[34:35], 1.0 op_sel_hi:[1,0] neg_lo:[1,0] neg_hi:[1,0]
	s_nop 0
	v_pk_mul_f32 v[34:35], v[34:35], v[38:39]
	global_load_ushort v201, v234, s[54:55]
	v_and_b32_e32 v39, 0xffff0000, v134
	v_lshlrev_b32_e32 v38, 16, v134
	v_pk_mul_f32 v[38:39], v[40:41], v[38:39]
	v_pk_mul_f32 v[40:41], v[36:37], v[34:35] op_sel_hi:[0,1]
	v_cvt_pk_bf16_f32 v37, v38, v39
	global_load_ushort v217, v234, s[60:61]
	v_add_u32_e32 v235, s76, v228
	v_cvt_pk_bf16_f32 v34, v34, v35
	ds_write_b16 v89, v37
	ds_write_b16_d16_hi v90, v37
	ds_write_b16 v89, v34 offset:17408
	ds_write_b16_d16_hi v90, v34 offset:17408
	global_load_ushort v186, v235, s[64:65]
	v_add_f32_e32 v35, v59, v153
	v_mul_f32_e32 v37, 0x3fb8aa3b, v47
	v_exp_f32_e32 v38, v37
	v_mul_f32_e32 v37, 0xbfb8aa3b, v35
	global_load_ushort v202, v235, s[54:55]
	v_mul_f32_e32 v35, 0x3fb8aa3b, v35
	v_exp_f32_e32 v42, v35
; template <bool OUT>
; __device__ void phase_hgrn(const Params& p, const bf16_t* Qh, const bf16_t* Vv, const _Float16* Lfb, bf16_t* Of, bf16_t* Ob, float* Sseg, float* Dlog, LAS unsigned char* lds) {
;     ...
;         const float eblast = __expf(blast);
;         unsigned kew[8], vw[8];
; #pragma unroll
;         for (int i = 0; i < 16; i += 2) {
;           float qt[2], kt[2], ke[2];
; #pragma unroll
;           for (int e = 0; e < 2; ++e) {
;             const float bb = offs + cs[i + e];
;             const float k = 1.f - __expf(lf[i + e]);
;             const float ken = k * __expf(-bb);
;             if constexpr (OUT) { qt[e] = bf2f(qr[i + e]) * __expf(bb); kt[e] = ken; }
;             ke[e] = ken * eblast;
;           }
;           if constexpr (OUT) {
;             const unsigned qp = pk2(qt[0], qt[1]), kp = pk2(kt[0], kt[1]);
;             const int s = 16 * tq + i;
;             *(LAS bf16_t*)(lds + QT + (s * 136 + dk) * 2) = (bf16_t)(qp & 0xffffu);
;             *(LAS bf16_t*)(lds + QT + ((s + 1) * 136 + dk) * 2) = (bf16_t)(qp >> 16);
;             *(LAS bf16_t*)(lds + KT + (s * 136 + dk) * 2) = (bf16_t)(kp & 0xffffu);
;             *(LAS bf16_t*)(lds + KT + ((s + 1) * 136 + dk) * 2) = (bf16_t)(kp >> 16);
;           }
;           kew[i >> 1] = pk2(ke[0], ke[1]);
;           vw[i >> 1] = (unsigned)vr[i] | ((unsigned)vr[i + 1] << 16);
;         }
;         *(LAS u32x4*)(lds + KE + (dk * 72 + 16 * tq) * 2) = (u32x4){kew[0], kew[1], kew[2], kew[3]};
;         *(LAS u32x4*)(lds + KE + (dk * 72 + 16 * tq + 8) * 2) = (u32x4){kew[4], kew[5], kew[6], kew[7]};
;         *(LAS u32x4*)(lds + VT + (dk * 72 + 16 * tq) * 2) = (u32x4){vw[0], vw[1], vw[2], vw[3]};
;         *(LAS u32x4*)(lds + VT + (dk * 72 + 16 * tq + 8) * 2) = (u32x4){vw[4], vw[5], vw[6], vw[7]};
;         if (tq == 0) *(LAS float*)(lds + DC + dk * 4) = eblast;
;         dsum += blast;
;       }
;       __syncthreads();
;       if (c + 1 < c_end) {
;         const int cn = c + 1;
;         const int rb = (cn < 4) ? b * 256 + (dir ? 255 - 64 * cn : 64 * cn) : NCTX + b * 8192 + (dir ? 8191 - 64 * (cn - 4) : 64 * (cn - 4));
;         const size_t o0 = (size_t)(rb + sgn * 16 * tq) * DM + h * 128 + dk;
; #pragma unroll
;         for (int i = 0; i < 16; ++i) { const size_t o = o0 + (ptrdiff_t)(sgn * i) * DM; lfr[i] = Lx[o]; if constexpr (OUT) qr[i] = Qh[o]; else qr[i] = 0; vr[i] = Vv[o]; }
	v_mul_f32_e32 v35, 0x3fb8aa3b, v56
	v_exp_f32_e32 v39, v35
	v_add_f32_e32 v35, v60, v153
	global_load_ushort v218, v235, s[60:61]
	v_add_u32_e32 v236, s78, v228
	v_cvt_pk_bf16_f32 v34, v40, v41
	v_exp_f32_e32 v40, v37
	v_mul_f32_e32 v37, 0xbfb8aa3b, v35
	v_exp_f32_e32 v41, v37
	v_mul_f32_e32 v35, 0x3fb8aa3b, v35
	global_load_ushort v187, v236, s[64:65]
	v_exp_f32_e32 v43, v35
	v_pk_add_f32 v[38:39], v[38:39], 1.0 op_sel_hi:[1,0] neg_lo:[1,0] neg_hi:[1,0]
	s_nop 0
	v_pk_mul_f32 v[38:39], v[38:39], v[40:41]
	v_and_b32_e32 v41, 0xffff0000, v135
	global_load_ushort v203, v236, s[54:55]
	v_lshlrev_b32_e32 v40, 16, v135
	v_pk_mul_f32 v[40:41], v[42:43], v[40:41]
	v_pk_mul_f32 v[42:43], v[36:37], v[38:39] op_sel_hi:[0,1]
	v_cvt_pk_bf16_f32 v35, v40, v41
	v_cvt_pk_bf16_f32 v37, v38, v39
	global_load_ushort v219, v236, s[60:61]
	v_add_u32_e32 v237, s80, v228
	ds_write_b16 v91, v35
	ds_write_b16_d16_hi v92, v35
	ds_write_b16 v91, v37 offset:17408
	ds_write_b16_d16_hi v92, v37 offset:17408
	global_load_ushort v188, v237, s[64:65]
	v_add_f32_e32 v37, v141, v153
	v_mul_f32_e32 v39, 0xbfb8aa3b, v37
	v_mul_f32_e32 v37, 0x3fb8aa3b, v37
	v_cvt_pk_bf16_f32 v35, v42, v43
	v_exp_f32_e32 v42, v37
	global_load_ushort v204, v237, s[54:55]
	v_mul_f32_e32 v37, 0x3fb8aa3b, v62
	v_mul_f32_e32 v38, 0x3fb8aa3b, v61
	v_exp_f32_e32 v40, v39
	v_exp_f32_e32 v39, v37
	v_add_f32_e32 v37, v142, v153
	global_load_ushort v220, v237, s[60:61]
	v_add_u32_e32 v230, s82, v228
	v_exp_f32_e32 v38, v38
	v_mul_f32_e32 v41, 0xbfb8aa3b, v37
	v_exp_f32_e32 v41, v41
	v_mul_f32_e32 v37, 0x3fb8aa3b, v37
	v_exp_f32_e32 v43, v37
	global_load_ushort v189, v230, s[64:65]
	v_pk_add_f32 v[38:39], v[38:39], 1.0 op_sel_hi:[1,0] neg_lo:[1,0] neg_hi:[1,0]
	s_nop 0
	v_pk_mul_f32 v[38:39], v[38:39], v[40:41]
	v_and_b32_e32 v41, 0xffff0000, v136
	global_load_ushort v205, v230, s[54:55]
	v_lshlrev_b32_e32 v40, 16, v136
	v_pk_mul_f32 v[40:41], v[42:43], v[40:41]
	v_pk_mul_f32 v[42:43], v[36:37], v[38:39] op_sel_hi:[0,1]
	v_cvt_pk_bf16_f32 v37, v40, v41
	v_cvt_pk_bf16_f32 v38, v38, v39
	global_load_ushort v221, v230, s[60:61]
	v_add_u32_e32 v231, s84, v228
	ds_write_b16 v93, v37
	ds_write_b16_d16_hi v94, v37
	ds_write_b16 v93, v38 offset:17408
	ds_write_b16_d16_hi v94, v38 offset:17408
	v_add_f32_e32 v37, v143, v153
	global_load_ushort v190, v231, s[64:65]
	v_mul_f32_e32 v39, 0x3fb8aa3b, v63
	v_exp_f32_e32 v40, v39
	v_mul_f32_e32 v39, 0xbfb8aa3b, v37
	v_mul_f32_e32 v37, 0x3fb8aa3b, v37
	v_exp_f32_e32 v44, v37
	global_load_ushort v206, v231, s[54:55]
	v_mul_f32_e32 v37, 0x3fb8aa3b, v140
	v_exp_f32_e32 v41, v37
	v_add_f32_e32 v37, v144, v153
	v_cvt_pk_bf16_f32 v38, v42, v43
	v_exp_f32_e32 v42, v39
	global_load_ushort v222, v231, s[60:61]
	v_add_u32_e32 v232, s86, v228
	v_mul_f32_e32 v39, 0xbfb8aa3b, v37
	v_exp_f32_e32 v43, v39
	v_mul_f32_e32 v37, 0x3fb8aa3b, v37
	v_exp_f32_e32 v45, v37
	global_load_ushort v191, v232, s[64:65]
	v_pk_add_f32 v[40:41], v[40:41], 1.0 op_sel_hi:[1,0] neg_lo:[1,0] neg_hi:[1,0]
	s_nop 0
	v_pk_mul_f32 v[40:41], v[40:41], v[42:43]
	v_and_b32_e32 v43, 0xffff0000, v137
	v_lshlrev_b32_e32 v42, 16, v137
	global_load_ushort v207, v232, s[54:55]
	v_pk_mul_f32 v[42:43], v[44:45], v[42:43]
	v_pk_mul_f32 v[44:45], v[36:37], v[40:41] op_sel_hi:[0,1]
	v_cvt_pk_bf16_f32 v37, v42, v43
	v_cvt_pk_bf16_f32 v39, v40, v41
	ds_write_b16 v95, v37
	global_load_ushort v223, v232, s[60:61]
	v_add_u32_e32 v233, s88, v228
	ds_write_b16_d16_hi v96, v37
	ds_write_b16 v95, v39 offset:17408
	ds_write_b16_d16_hi v96, v39 offset:17408
	v_add_f32_e32 v37, v149, v153
	v_mul_f32_e32 v41, 0xbfb8aa3b, v37
	global_load_ushort v192, v233, s[64:65]
	v_mul_f32_e32 v37, 0x3fb8aa3b, v37
	v_cvt_pk_bf16_f32 v39, v44, v45
	v_exp_f32_e32 v44, v37
	v_mul_f32_e32 v37, 0x3fb8aa3b, v146
	v_mul_f32_e32 v40, 0x3fb8aa3b, v145
	global_load_ushort v208, v233, s[54:55]
	v_exp_f32_e32 v42, v41
	v_exp_f32_e32 v41, v37
	v_add_f32_e32 v37, v150, v153
	v_exp_f32_e32 v40, v40
	global_load_ushort v224, v233, s[60:61]
	v_add_u32_e32 v234, s90, v228
	v_mul_f32_e32 v43, 0xbfb8aa3b, v37
	v_exp_f32_e32 v43, v43
	v_mul_f32_e32 v37, 0x3fb8aa3b, v37
	v_exp_f32_e32 v45, v37
	v_pk_add_f32 v[40:41], v[40:41], 1.0 op_sel_hi:[1,0] neg_lo:[1,0] neg_hi:[1,0]
	global_load_ushort v193, v234, s[64:65]
	s_nop 0
	v_pk_mul_f32 v[40:41], v[40:41], v[42:43]
	v_and_b32_e32 v43, 0xffff0000, v138
	v_lshlrev_b32_e32 v42, 16, v138
	v_pk_mul_f32 v[42:43], v[44:45], v[42:43]
	global_load_ushort v209, v234, s[54:55]
	v_pk_mul_f32 v[44:45], v[36:37], v[40:41] op_sel_hi:[0,1]
	v_cvt_pk_bf16_f32 v37, v42, v43
	v_cvt_pk_bf16_f32 v40, v40, v41
	ds_write_b16 v97, v37
	ds_write_b16_d16_hi v98, v37
	global_load_ushort v225, v234, s[60:61]
	v_add_u32_e32 v235, s92, v228
	ds_write_b16 v97, v40 offset:17408
	ds_write_b16_d16_hi v98, v40 offset:17408
	v_add_f32_e32 v37, v151, v153
	v_mul_f32_e32 v41, 0x3fb8aa3b, v147
	v_exp_f32_e32 v42, v41
	global_load_ushort v194, v235, s[64:65]
	v_mul_f32_e32 v41, 0xbfb8aa3b, v37
	v_mul_f32_e32 v37, 0x3fb8aa3b, v37
	v_exp_f32_e32 v46, v37
	v_mul_f32_e32 v37, 0x3fb8aa3b, v148
	global_load_ushort v210, v235, s[54:55]
	v_exp_f32_e32 v43, v37
	v_add_f32_e32 v37, v152, v153
	v_cvt_pk_bf16_f32 v40, v44, v45
	v_exp_f32_e32 v44, v41
	v_mul_f32_e32 v41, 0xbfb8aa3b, v37
	global_load_ushort v226, v235, s[60:61]
	v_add_u32_e32 v236, s94, v228
	v_exp_f32_e32 v45, v41
	v_mul_f32_e32 v37, 0x3fb8aa3b, v37
	v_exp_f32_e32 v47, v37
	v_pk_add_f32 v[42:43], v[42:43], 1.0 op_sel_hi:[1,0] neg_lo:[1,0] neg_hi:[1,0]
	s_nop 0
	global_load_ushort v195, v236, s[64:65]
	v_pk_mul_f32 v[42:43], v[42:43], v[44:45]
	v_and_b32_e32 v45, 0xffff0000, v139
	v_lshlrev_b32_e32 v44, 16, v139
	v_pk_mul_f32 v[44:45], v[46:47], v[44:45]
	v_pk_mul_f32 v[46:47], v[36:37], v[42:43] op_sel_hi:[0,1]
	global_load_ushort v211, v236, s[54:55]
	v_cvt_pk_bf16_f32 v37, v44, v45
	v_cvt_pk_bf16_f32 v41, v42, v43
	ds_write_b16 v99, v37
	ds_write_b16_d16_hi v100, v37
	ds_write_b16 v99, v41 offset:17408
	global_load_ushort v227, v236, s[60:61]
	ds_write_b16_d16_hi v100, v41 offset:17408
	v_cvt_pk_bf16_f32 v41, v46, v47
	ds_write_b128 v101, v[32:35] offset:34816
	ds_write_b128 v101, v[38:41] offset:34832
	ds_write_b128 v101, v[48:51] offset:53248
	ds_write_b128 v101, v[52:55] offset:53264
	s_and_saveexec_b64 s[0:1], s[6:7]
	v_add_u32_e32 v32, 0, v79
	v_add_u32_e32 v32, 0x1c400, v32
	ds_write_b32 v32, v36
	s_or_b64 exec, exec, s[0:1]
	s_add_i32 s4, s34, 1
	s_cmp_ge_u32 s4, s31
	s_waitcnt lgkmcnt(0)
	s_barrier

; __global__ void __launch_bounds__(NTHR, 2) mega(Params p, int ph0, int ph1) {
;   extern __shared__ __attribute__((aligned(16))) bf16_t shm[];
	.amdhsa_kernel _Z4mega6Paramsii
		.amdhsa_group_segment_fixed_size 0
		.amdhsa_private_segment_fixed_size 0
		.amdhsa_kernarg_size 616
		.amdhsa_user_sgpr_count 2
		.amdhsa_user_sgpr_dispatch_ptr 0
		.amdhsa_user_sgpr_queue_ptr 0
		.amdhsa_user_sgpr_kernarg_segment_ptr 1
		.amdhsa_user_sgpr_dispatch_id 0
		.amdhsa_user_sgpr_kernarg_preload_length 0
		.amdhsa_user_sgpr_kernarg_preload_offset 0
		.amdhsa_user_sgpr_private_segment_size 0
		.amdhsa_uses_dynamic_stack 0
		.amdhsa_enable_private_segment 0
		.amdhsa_system_sgpr_workgroup_id_x 1
		.amdhsa_system_sgpr_workgroup_id_y 0
		.amdhsa_system_sgpr_workgroup_id_z 0
		.amdhsa_system_sgpr_workgroup_info 0
		.amdhsa_system_vgpr_workitem_id 2
		.amdhsa_next_free_vgpr 256
		.amdhsa_next_free_sgpr 102
		.amdhsa_accum_offset 256
		.amdhsa_reserve_vcc 1
		.amdhsa_float_round_mode_32 0
		.amdhsa_float_round_mode_16_64 0
		.amdhsa_float_denorm_mode_32 3
		.amdhsa_float_denorm_mode_16_64 3
		.amdhsa_dx10_clamp 1
		.amdhsa_ieee_mode 1
		.amdhsa_fp16_overflow 0
		.amdhsa_tg_split 0
		.amdhsa_exception_fp_ieee_invalid_op 0
		.amdhsa_exception_fp_denorm_src 0
		.amdhsa_exception_fp_ieee_div_zero 0
		.amdhsa_exception_fp_ieee_overflow 0
		.amdhsa_exception_fp_ieee_underflow 0
		.amdhsa_exception_fp_ieee_inexact 0
		.amdhsa_exception_int_div_zero 0
	.end_amdhsa_kernel

; __global__ void __launch_bounds__(NTHR, 2) mega(Params p, int ph0, int ph1) {
;   extern __shared__ __attribute__((aligned(16))) bf16_t shm[];
amdhsa.kernels:
  - .agpr_count:     0
    .args:
      - .offset:         0
        .size:           352
        .value_kind:     by_value
      - .offset:         352
        .size:           4
        .value_kind:     by_value
      - .offset:         356
        .size:           4
        .value_kind:     by_value
      - .offset:         360
        .size:           4
        .value_kind:     hidden_block_count_x
      - .offset:         364
        .size:           4
        .value_kind:     hidden_block_count_y
      - .offset:         368
        .size:           4
        .value_kind:     hidden_block_count_z
      - .offset:         372
        .size:           2
        .value_kind:     hidden_group_size_x
      - .offset:         374
        .size:           2
        .value_kind:     hidden_group_size_y
      - .offset:         376
        .size:           2
        .value_kind:     hidden_group_size_z
      - .offset:         378
        .size:           2
        .value_kind:     hidden_remainder_x
      - .offset:         380
        .size:           2
        .value_kind:     hidden_remainder_y
      - .offset:         382
        .size:           2
        .value_kind:     hidden_remainder_z
      - .offset:         400
        .size:           8
        .value_kind:     hidden_global_offset_x
      - .offset:         408
        .size:           8
        .value_kind:     hidden_global_offset_y
      - .offset:         416
        .size:           8
        .value_kind:     hidden_global_offset_z
      - .offset:         424
        .size:           2
        .value_kind:     hidden_grid_dims
      - .offset:         448
        .size:           8
        .value_kind:     hidden_multigrid_sync_arg
      - .offset:         480
        .size:           4
        .value_kind:     hidden_dynamic_lds_size
    .group_segment_fixed_size: 0
    .kernarg_segment_align: 8
    .kernarg_segment_size: 616
    .language:       OpenCL C
    .language_version:
      - 2
      - 0
    .max_flat_workgroup_size: 512
    .name:           _Z4mega6Paramsii
    .private_segment_fixed_size: 0
    .sgpr_count:     108
    .sgpr_spill_count: 41
    .symbol:         _Z4mega6Paramsii.kd
    .uniform_work_group_size: 1
    .uses_dynamic_stack: false
    .vgpr_count:     256
    .vgpr_spill_count: 0
    .wavefront_size: 64
